# speedup vs baseline: 1.0556x; 1.0049x over previous
; __device__ __forceinline__ u32x2 pack4(float a, float b, float c, float d) { return u32x2{cvtpk(a, b), cvtpk(c, d)}; }
; __device__ __forceinline__ u32x2 pack4(const f32x4& v) { return u32x2{cvtpk(v[0], v[1]), cvtpk(v[2], v[3])}; }
; #define SBAR() __builtin_amdgcn_sched_barrier(0)
; __global__ void __launch_bounds__(512) fwd_megakernel(Params p) {
;     ...
;         for (int ai = 0; ai < 2; ++ai) { SBAR();
;           u32x2 hv[4][2][2];
;           #pragma unroll
;           for (int m = 0; m < 4; ++m) {
;             const bf16* hr = p_h1b + (long)(brow + ai * 128 + wr * 64 + m * 16 + fr) * DM + pn * 256 + wc * 32 + fq * 4;
;             #pragma unroll
;             for (int bj = 0; bj < 2; ++bj)
;               #pragma unroll
;               for (int n = 0; n < 2; ++n) hv[m][bj][n] = *reinterpret_cast<const u32x2*>(hr + bj * 128 + n * 16);
;           }
;           SBAR();
;           #pragma unroll
;           for (int m = 0; m < 4; ++m) {
;             int lrow = ai * 128 + wr * 64 + m * 16 + fr, row = brow + lrow; float ss = 0.f;
;             bf16* od = p_h2b + (long)row * DM + pn * 256 + wc * 32 + fq * 4;
;             #pragma unroll
;             for (int bj = 0; bj < 2; ++bj)
;               #pragma unroll
;               for (int n = 0; n < 2; ++n) {
;                 const u32x2 hw = hv[m][bj][n];
;                 f32x4 v = acc[ai][bj][m][n];
;                 v[0] += __uint_as_float(hw[0] << 16); v[1] += __uint_as_float(hw[0] & 0xffff0000u);
;                 v[2] += __uint_as_float(hw[1] << 16); v[3] += __uint_as_float(hw[1] & 0xffff0000u);
;                 ss += (v[0] * v[0] + v[1] * v[1]) + (v[2] * v[2] + v[3] * v[3]);
;                 *reinterpret_cast<u32x2*>(od + bj * 128 + n * 16) = pack4(v);
;               }
;             ss += __shfl_xor(ss, 16); ss += __shfl_xor(ss, 32);
;             if (fq == 0) red[wc * 256 + lrow] = ss;
;           }
.LBB0_749:
	v_mov_b32_e32 v128, v252
	s_waitcnt lgkmcnt(0)
	s_barrier
	s_nop 0
	v_bfe_u32 v162, v128, 6, 2
	v_and_b32_e32 v130, 15, v128
	v_bfe_u32 v163, v128, 4, 2
	v_ashrrev_i32_e32 v128, 2, v128
	v_and_or_b32 v161, v128, s51, v130
	v_cmp_eq_u32_e32 vcc, 0, v163
	v_lshl_add_u32 v176, v162, 10, s69
	s_ashr_i32 s31, s30, 31
	s_lshl_b64 s[0:1], s[30:31], 1
	s_add_u32 s36, s26, s0
	v_add_u32_e32 v130, s29, v161
	s_addc_u32 s37, s27, s1
	v_lshlrev_b32_e32 v128, 6, v162
	v_lshl_add_u64 v[132:133], s[36:37], 0, v[128:129]
	v_lshlrev_b32_e32 v164, 3, v163
	v_mov_b32_e32 v165, v129
	v_ashrrev_i32_e32 v131, 31, v130
	v_lshl_add_u64 v[132:133], v[132:133], 0, v[164:165]
	v_lshlrev_b64 v[166:167], 11, v[130:131]
	v_lshl_add_u64 v[134:135], v[132:133], 0, v[166:167]
	v_bfe_u32 v208, v252, 4, 1
	v_mul_u32_u24_e32 v208, 24, v208
	v_mov_b32_e32 v209, 0
	v_lshl_add_u64 v[198:199], v[134:135], 0, v[208:209]
	global_load_dwordx4 v[168:171], v[198:199], off
	global_load_dwordx4 v[172:175], v[198:199], off offset:256
	v_or_b32_e32 v134, 16, v130
	v_ashrrev_i32_e32 v135, 31, v134
	v_lshlrev_b64 v[134:135], 11, v[134:135]
	v_lshl_add_u64 v[134:135], v[132:133], 0, v[134:135]
	v_lshl_add_u64 v[198:199], v[134:135], 0, v[208:209]
	global_load_dwordx4 v[156:159], v[198:199], off
	global_load_dwordx4 v[152:155], v[198:199], off offset:256
	v_or_b32_e32 v134, 32, v130
	v_ashrrev_i32_e32 v135, 31, v134
	v_lshlrev_b64 v[134:135], 11, v[134:135]
	v_lshl_add_u64 v[134:135], v[132:133], 0, v[134:135]
	v_lshl_add_u64 v[198:199], v[134:135], 0, v[208:209]
	global_load_dwordx4 v[148:151], v[198:199], off
	global_load_dwordx4 v[136:139], v[198:199], off offset:256
	v_or_b32_e32 v134, 48, v130
	v_ashrrev_i32_e32 v135, 31, v134
	v_lshlrev_b64 v[134:135], 11, v[134:135]
	v_lshl_add_u64 v[134:135], v[132:133], 0, v[134:135]
	v_lshl_add_u64 v[198:199], v[134:135], 0, v[208:209]
	global_load_dwordx4 v[140:143], v[198:199], off
	global_load_dwordx4 v[180:183], v[198:199], off offset:256
	v_lshl_add_u64 v[166:167], s[26:27], 0, v[166:167]
	v_lshl_add_u64 v[166:167], v[166:167], 0, s[0:1]
	v_lshl_add_u64 v[166:167], v[166:167], 0, v[128:129]
	s_waitcnt vmcnt(0)
	v_permlane16_swap_b32_e32 v168, v170
	v_permlane16_swap_b32_e32 v169, v171
	v_permlane16_swap_b32_e32 v172, v174
	v_permlane16_swap_b32_e32 v173, v175
	v_permlane16_swap_b32_e32 v156, v158
	v_permlane16_swap_b32_e32 v157, v159
	v_permlane16_swap_b32_e32 v152, v154
	v_permlane16_swap_b32_e32 v153, v155
	v_permlane16_swap_b32_e32 v148, v150
	v_permlane16_swap_b32_e32 v149, v151
	v_permlane16_swap_b32_e32 v136, v138
	v_permlane16_swap_b32_e32 v137, v139
	v_permlane16_swap_b32_e32 v140, v142
	v_permlane16_swap_b32_e32 v141, v143
	v_permlane16_swap_b32_e32 v180, v182
	v_permlane16_swap_b32_e32 v181, v183
	v_swap_b32 v156, v158
	v_swap_b32 v157, v159
	v_swap_b32 v152, v154
	v_swap_b32 v153, v155
	v_swap_b32 v148, v150
	v_swap_b32 v149, v151
	v_swap_b32 v138, v142
	v_swap_b32 v139, v143
	v_mov_b32_e32 v146, v136
	v_mov_b32_e32 v147, v137
	v_mov_b32_e32 v136, v180
	v_mov_b32_e32 v137, v181
	v_mov_b32_e32 v134, v182
	v_mov_b32_e32 v135, v183
	v_lshlrev_b32_e32 v128, 16, v168
	v_add_f32_e32 v124, v124, v128
	v_and_b32_e32 v128, 0xffff0000, v168
	v_add_f32_e32 v125, v125, v128
	v_lshlrev_b32_e32 v128, 16, v169
	v_add_f32_e32 v126, v126, v128
	v_and_b32_e32 v128, 0xffff0000, v169
	v_add_f32_e32 v127, v127, v128
	v_mul_f32_e32 v128, v125, v125
	v_lshl_add_u64 v[164:165], v[166:167], 0, v[164:165]
	v_fmac_f32_e32 v128, v124, v124
	v_cvt_pk_bf16_f32 v124, v124, v125
	v_cvt_pk_bf16_f32 v125, v126, v127
	v_mov_b32_e32 v200, v124
	v_mov_b32_e32 v201, v125
	v_lshlrev_b32_e32 v124, 16, v170
	v_add_f32_e32 v116, v116, v124
	v_and_b32_e32 v124, 0xffff0000, v170
	v_add_f32_e32 v117, v117, v124
	v_lshlrev_b32_e32 v124, 16, v171
	v_add_f32_e32 v118, v118, v124
	v_and_b32_e32 v124, 0xffff0000, v171
	v_add_f32_e32 v119, v119, v124
	v_mul_f32_e32 v124, v117, v117
	v_fmac_f32_e32 v124, v116, v116
	v_mul_f32_e32 v125, v119, v119
	v_cvt_pk_bf16_f32 v116, v116, v117
	v_cvt_pk_bf16_f32 v117, v118, v119
	v_and_b32_e32 v119, 0xffff0000, v172
	v_fmac_f32_e32 v125, v118, v118
	v_lshlrev_b32_e32 v118, 16, v172
	v_add_f32_e32 v119, v121, v119
	v_and_b32_e32 v121, 0xffff0000, v173
	v_add_f32_e32 v118, v120, v118
	v_lshlrev_b32_e32 v120, 16, v173
	v_add_f32_e32 v121, v123, v121
	v_mul_f32_e32 v131, v127, v127
	v_add_f32_e32 v120, v122, v120
	v_mul_f32_e32 v122, v119, v119
	v_mul_f32_e32 v123, v121, v121
	v_fmac_f32_e32 v131, v126, v126
	v_fmac_f32_e32 v122, v118, v118
	v_fmac_f32_e32 v123, v120, v120
	v_add_f32_e32 v128, v128, v131
	v_add_f32_e32 v124, v124, v125
	v_add_f32_e32 v122, v122, v123
	v_lshlrev_b32_e32 v123, 16, v174
	v_add_f32_e32 v124, v128, v124
	v_add_f32_e32 v123, v112, v123
	v_and_b32_e32 v112, 0xffff0000, v174
	v_add_f32_e32 v122, v124, v122
	v_add_f32_e32 v124, v113, v112
	v_lshlrev_b32_e32 v112, 16, v175
	v_add_f32_e32 v114, v114, v112
	v_and_b32_e32 v112, 0xffff0000, v175
	v_add_f32_e32 v125, v115, v112
	v_mul_f32_e32 v112, v124, v124
	v_mul_f32_e32 v113, v125, v125
	v_fmac_f32_e32 v112, v123, v123
	v_fmac_f32_e32 v113, v114, v114
	v_add_f32_e32 v112, v112, v113
	v_and_b32_e32 v113, 64, v145
	v_add_f32_e32 v122, v122, v112
	v_xor_b32_e32 v112, 16, v145
	v_add_u32_e32 v126, 64, v113
	v_cmp_lt_i32_e64 s[0:1], v112, v126
	v_mov_b32_e32 v202, v116
	v_mov_b32_e32 v203, v117
	v_bfe_u32 v206, v252, 4, 1
	v_mul_u32_u24_e32 v206, 24, v206
	v_mov_b32_e32 v207, 0
	v_lshl_add_u64 v[204:205], v[164:165], 0, v[206:207]
	v_permlane16_swap_b32_e32 v200, v202
	v_permlane16_swap_b32_e32 v201, v203
	global_store_dwordx4 v[204:205], v[200:203], off
	s_nop 1
	s_nop 0
	v_cndmask_b32_e64 v112, v145, v112, s[0:1]
	v_lshlrev_b32_e32 v115, 2, v112
	ds_bpermute_b32 v127, v115, v122
	v_cvt_pk_bf16_f32 v112, v118, v119
	v_cvt_pk_bf16_f32 v113, v120, v121
	v_mov_b32_e32 v200, v112
	v_mov_b32_e32 v201, v113
	v_xor_b32_e32 v113, 32, v145
	v_cmp_lt_i32_e64 s[0:1], v113, v126
	s_waitcnt lgkmcnt(0)
	v_add_f32_e32 v112, v122, v127
	v_cvt_pk_bf16_f32 v118, v123, v124
	v_cvt_pk_bf16_f32 v119, v114, v125
	v_lshl_add_u32 v114, v161, 2, v176
	v_cndmask_b32_e64 v113, v145, v113, s[0:1]
	v_lshlrev_b32_e32 v116, 2, v113
	ds_bpermute_b32 v113, v116, v112
	v_mov_b32_e32 v202, v118
	v_mov_b32_e32 v203, v119
	v_bfe_u32 v206, v252, 4, 1
	v_mul_u32_u24_e32 v206, 24, v206
	v_mov_b32_e32 v207, 0
	v_lshl_add_u64 v[204:205], v[164:165], 0, v[206:207]
	v_permlane16_swap_b32_e32 v200, v202
	v_permlane16_swap_b32_e32 v201, v203
	global_store_dwordx4 v[204:205], v[200:203], off offset:256
	s_nop 1
	s_and_saveexec_b64 s[0:1], vcc
	s_cbranch_execz .LBB0_751
	s_waitcnt lgkmcnt(0)
	v_add_f32_e32 v112, v112, v113
	ds_write_b32 v114, v112

; __device__ __forceinline__ u32x2 pack4(float a, float b, float c, float d) { return u32x2{cvtpk(a, b), cvtpk(c, d)}; }
; __device__ __forceinline__ u32x2 pack4(const f32x4& v) { return u32x2{cvtpk(v[0], v[1]), cvtpk(v[2], v[3])}; }
; #define SBAR() __builtin_amdgcn_sched_barrier(0)
; __global__ void __launch_bounds__(512) fwd_megakernel(Params p) {
;     ...
;         for (int ai = 0; ai < 2; ++ai) { SBAR();
;           u32x2 hv[4][2][2];
;           #pragma unroll
;           for (int m = 0; m < 4; ++m) {
;             const bf16* hr = p_h1b + (long)(brow + ai * 128 + wr * 64 + m * 16 + fr) * DM + pn * 256 + wc * 32 + fq * 4;
;             #pragma unroll
;             for (int bj = 0; bj < 2; ++bj)
;               #pragma unroll
;               for (int n = 0; n < 2; ++n) hv[m][bj][n] = *reinterpret_cast<const u32x2*>(hr + bj * 128 + n * 16);
;           }
;           SBAR();
;           #pragma unroll
;           for (int m = 0; m < 4; ++m) {
;             int lrow = ai * 128 + wr * 64 + m * 16 + fr, row = brow + lrow; float ss = 0.f;
;             bf16* od = p_h2b + (long)row * DM + pn * 256 + wc * 32 + fq * 4;
;             #pragma unroll
;             for (int bj = 0; bj < 2; ++bj)
;               #pragma unroll
;               for (int n = 0; n < 2; ++n) {
;                 const u32x2 hw = hv[m][bj][n];
;                 f32x4 v = acc[ai][bj][m][n];
;                 v[0] += __uint_as_float(hw[0] << 16); v[1] += __uint_as_float(hw[0] & 0xffff0000u);
;                 v[2] += __uint_as_float(hw[1] << 16); v[3] += __uint_as_float(hw[1] & 0xffff0000u);
;                 ss += (v[0] * v[0] + v[1] * v[1]) + (v[2] * v[2] + v[3] * v[3]);
;                 *reinterpret_cast<u32x2*>(od + bj * 128 + n * 16) = pack4(v);
;               }
;             ss += __shfl_xor(ss, 16); ss += __shfl_xor(ss, 32);
;             if (fq == 0) red[wc * 256 + lrow] = ss;
;           }
.LBB0_757:
	s_or_b64 exec, exec, s[0:1]
	v_add_u32_e32 v64, 0x80, v130
	s_waitcnt lgkmcnt(0)
	v_ashrrev_i32_e32 v65, 31, v64
	v_lshlrev_b64 v[94:95], 11, v[64:65]
	v_lshl_add_u64 v[64:65], v[132:133], 0, v[94:95]
	v_bfe_u32 v208, v252, 4, 1
	v_mul_u32_u24_e32 v208, 24, v208
	v_mov_b32_e32 v209, 0
	v_lshl_add_u64 v[198:199], v[64:65], 0, v[208:209]
	global_load_dwordx4 v[96:99], v[198:199], off
	global_load_dwordx4 v[100:103], v[198:199], off offset:256
	v_add_u32_e32 v64, 0x90, v130
	v_ashrrev_i32_e32 v65, 31, v64
	v_lshlrev_b64 v[92:93], 11, v[64:65]
	v_add_u32_e32 v82, 0xa0, v130
	v_lshl_add_u64 v[64:65], v[132:133], 0, v[92:93]
	v_ashrrev_i32_e32 v83, 31, v82
	v_lshl_add_u64 v[198:199], v[64:65], 0, v[208:209]
	global_load_dwordx4 v[88:91], v[198:199], off
	global_load_dwordx4 v[84:87], v[198:199], off offset:256
	v_lshlrev_b64 v[64:65], 11, v[82:83]
	v_add_u32_e32 v72, 0xb0, v130
	v_lshl_add_u64 v[64:65], v[132:133], 0, v[64:65]
	v_ashrrev_i32_e32 v73, 31, v72
	v_lshl_add_u64 v[198:199], v[64:65], 0, v[208:209]
	global_load_dwordx4 v[180:183], v[198:199], off
	global_load_dwordx4 v[76:79], v[198:199], off offset:256
	v_lshlrev_b64 v[64:65], 11, v[72:73]
	v_lshl_add_u64 v[64:65], v[132:133], 0, v[64:65]
	v_lshl_add_u64 v[198:199], v[64:65], 0, v[208:209]
	global_load_dwordx4 v[68:71], v[198:199], off
	global_load_dwordx4 v[64:67], v[198:199], off offset:256
	s_waitcnt vmcnt(0)
	v_permlane16_swap_b32_e32 v96, v98
	v_permlane16_swap_b32_e32 v97, v99
	v_permlane16_swap_b32_e32 v100, v102
	v_permlane16_swap_b32_e32 v101, v103
	v_permlane16_swap_b32_e32 v88, v90
	v_permlane16_swap_b32_e32 v89, v91
	v_permlane16_swap_b32_e32 v84, v86
	v_permlane16_swap_b32_e32 v85, v87
	v_permlane16_swap_b32_e32 v180, v182
	v_permlane16_swap_b32_e32 v181, v183
	v_permlane16_swap_b32_e32 v76, v78
	v_permlane16_swap_b32_e32 v77, v79
	v_permlane16_swap_b32_e32 v68, v70
	v_permlane16_swap_b32_e32 v69, v71
	v_permlane16_swap_b32_e32 v64, v66
	v_permlane16_swap_b32_e32 v65, v67
	v_swap_b32 v88, v90
	v_swap_b32 v89, v91
	v_swap_b32 v84, v86
	v_swap_b32 v85, v87
	v_swap_b32 v68, v70
	v_swap_b32 v69, v71
	v_swap_b32 v64, v66
	v_swap_b32 v65, v67
	v_mov_b32_e32 v74, v78
	v_mov_b32_e32 v75, v79
	v_mov_b32_e32 v78, v182
	v_mov_b32_e32 v79, v183
	v_mov_b32_e32 v80, v180
	v_mov_b32_e32 v81, v181
	v_lshlrev_b32_e32 v104, 16, v96
	v_and_b32_e32 v96, 0xffff0000, v96
	v_lshl_add_u64 v[94:95], s[26:27], 0, v[94:95]
	v_add_f32_e32 v61, v61, v96
	v_lshlrev_b32_e32 v96, 16, v97
	v_lshl_add_u64 v[94:95], s[30:31], 1, v[94:95]
	v_add_f32_e32 v62, v62, v96
	v_and_b32_e32 v96, 0xffff0000, v97
	v_lshl_add_u64 v[94:95], v[94:95], 0, v[128:129]
	v_add_f32_e32 v60, v60, v104
	v_add_f32_e32 v63, v63, v96
	v_mul_f32_e32 v96, v61, v61
	v_lshl_add_u64 v[94:95], v[94:95], 0, v[112:113]
	v_fmac_f32_e32 v96, v60, v60
	v_cvt_pk_bf16_f32 v60, v60, v61
	v_cvt_pk_bf16_f32 v61, v62, v63
	v_mov_b32_e32 v200, v60
	v_mov_b32_e32 v201, v61
	s_waitcnt vmcnt(14)
	v_lshlrev_b32_e32 v60, 16, v98
	v_add_f32_e32 v56, v56, v60
	v_and_b32_e32 v60, 0xffff0000, v98
	v_add_f32_e32 v57, v57, v60
	v_lshlrev_b32_e32 v60, 16, v99
	v_add_f32_e32 v58, v58, v60
	v_and_b32_e32 v60, 0xffff0000, v99
	v_add_f32_e32 v59, v59, v60
	v_mul_f32_e32 v60, v57, v57
	v_fmac_f32_e32 v60, v56, v56
	v_cvt_pk_bf16_f32 v56, v56, v57
	s_waitcnt vmcnt(13)
	v_lshlrev_b32_e32 v57, 16, v100
	v_add_f32_e32 v52, v52, v57
	v_and_b32_e32 v57, 0xffff0000, v100
	v_add_f32_e32 v53, v53, v57
	v_lshlrev_b32_e32 v57, 16, v101
	v_mul_f32_e32 v61, v59, v59
	v_add_f32_e32 v54, v54, v57
	v_and_b32_e32 v57, 0xffff0000, v101
	v_mul_f32_e32 v97, v63, v63
	v_fmac_f32_e32 v61, v58, v58
	v_add_f32_e32 v55, v55, v57
	v_fmac_f32_e32 v97, v62, v62
	v_add_f32_e32 v60, v60, v61
	v_mul_f32_e32 v57, v53, v53
	v_mul_f32_e32 v61, v55, v55
	v_add_f32_e32 v96, v96, v97
	v_fmac_f32_e32 v57, v52, v52
	v_fmac_f32_e32 v61, v54, v54
	v_add_f32_e32 v60, v96, v60
	v_add_f32_e32 v57, v57, v61
	v_add_f32_e32 v57, v60, v57
	s_waitcnt vmcnt(12)
	v_lshlrev_b32_e32 v60, 16, v102
	v_add_f32_e32 v60, v48, v60
	v_and_b32_e32 v48, 0xffff0000, v102
	v_add_f32_e32 v61, v49, v48
	v_lshlrev_b32_e32 v48, 16, v103
	v_add_f32_e32 v62, v50, v48
	v_and_b32_e32 v48, 0xffff0000, v103
	v_add_f32_e32 v63, v51, v48
	v_mul_f32_e32 v48, v61, v61
	v_mul_f32_e32 v49, v63, v63
	v_fmac_f32_e32 v48, v60, v60
	v_fmac_f32_e32 v49, v62, v62
	v_add_f32_e32 v48, v48, v49
	v_add_f32_e32 v48, v57, v48
	ds_bpermute_b32 v49, v115, v48
	v_cvt_pk_bf16_f32 v57, v58, v59
	v_mov_b32_e32 v202, v56
	v_mov_b32_e32 v203, v57
	v_bfe_u32 v206, v252, 4, 1
	v_mul_u32_u24_e32 v206, 24, v206
	v_mov_b32_e32 v207, 0
	v_lshl_add_u64 v[204:205], v[94:95], 0, v[206:207]
	v_permlane16_swap_b32_e32 v200, v202
	v_permlane16_swap_b32_e32 v201, v203
	global_store_dwordx4 v[204:205], v[200:203], off
	s_nop 1
	v_cvt_pk_bf16_f32 v50, v52, v53
	v_cvt_pk_bf16_f32 v51, v54, v55
	s_waitcnt lgkmcnt(0)
	v_add_f32_e32 v48, v48, v49
	ds_bpermute_b32 v49, v116, v48
	v_mov_b32_e32 v200, v50
	v_mov_b32_e32 v201, v51
	v_cvt_pk_bf16_f32 v50, v60, v61
	v_cvt_pk_bf16_f32 v51, v62, v63
	v_mov_b32_e32 v202, v50
	v_mov_b32_e32 v203, v51
	v_bfe_u32 v206, v252, 4, 1
	v_mul_u32_u24_e32 v206, 24, v206
	v_mov_b32_e32 v207, 0
	v_lshl_add_u64 v[204:205], v[94:95], 0, v[206:207]
	v_permlane16_swap_b32_e32 v200, v202
	v_permlane16_swap_b32_e32 v201, v203
	global_store_dwordx4 v[204:205], v[200:203], off offset:256
	s_nop 1
	s_and_saveexec_b64 s[0:1], vcc
	s_cbranch_execz .LBB0_759
	s_waitcnt lgkmcnt(0)
	v_add_f32_e32 v48, v48, v49
	ds_write_b32 v114, v48 offset:512
